# stack on v67: P5 epilogue loads nt, P0 write-through stores, rmsnorm norm-weight hoist, SEAM3 producer-XCC wait
# speedup vs baseline: 1.0125x; 1.0093x over previous
; __device__ __forceinline__ void p0_prologue(const Ptrs& P, LAS unsigned char* lds, int vcu, int G) {
;     ...
;     for (int m = gw; m < TT; m += 2 * NGW) {
;         const int m2 = (m + NGW < TT) ? m + NGW : m;
;         const f32x4* xr = (const f32x4*)(P.x + (size_t)m * DM) + lane; const f32x4* xr2 = (const f32x4*)(P.x + (size_t)m2 * DM) + lane; f32x4 v[4], v2[4]; float s = 0.f, s2 = 0.f;
; #pragma unroll
;         for (int j = 0; j < 4; ++j) { v[j] = xr[64 * j]; v2[j] = xr2[64 * j]; }
; #pragma unroll
;         for (int j = 0; j < 4; ++j) { s += (v[j].x * v[j].x + v[j].y * v[j].y) + (v[j].z * v[j].z + v[j].w * v[j].w); s2 += (v2[j].x * v2[j].x + v2[j].y * v2[j].y) + (v2[j].z * v2[j].z + v2[j].w * v2[j].w); }
;         const float rstd = rsqrtf(wave_sum(s) * (1.0f / DM) + NORM_EPS), rstd2 = rsqrtf(wave_sum(s2) * (1.0f / DM) + NORM_EPS);
.LBB0_57:
	s_add_i32 s8, s0, s17
	s_cmpk_lt_i32 s8, 0x4000
	s_cselect_b32 s10, s8, s0
	s_ashr_i32 s1, s0, 31
	s_lshl_b64 s[12:13], s[0:1], 12
	s_ashr_i32 s11, s10, 31
	v_lshl_add_u64 v[22:23], v[2:3], 0, s[12:13]
	s_lshl_b64 s[12:13], s[10:11], 12
	global_load_dwordx4 v[18:21], v[22:23], off nt
	global_load_dwordx4 v[26:29], v[22:23], off offset:1024 nt
	global_load_dwordx4 v[30:33], v[22:23], off offset:3072 nt
	global_load_dwordx4 v[34:37], v[22:23], off offset:2048 nt
	v_lshl_add_u64 v[22:23], v[2:3], 0, s[12:13]
	global_load_dwordx4 v[38:41], v[22:23], off nt
	global_load_dwordx4 v[42:45], v[22:23], off offset:1024 nt
	global_load_dwordx4 v[46:49], v[22:23], off offset:3072 nt
	global_load_dwordx4 v[50:53], v[22:23], off offset:2048 nt
	s_lshl_b64 s[0:1], s[0:1], 11
	v_lshl_add_u64 v[54:55], v[0:1], 0, s[0:1]
	s_lshl_b64 s[0:1], s[10:11], 11
	v_lshl_add_u64 v[56:57], v[0:1], 0, s[0:1]
	s_waitcnt vmcnt(7)
	v_pk_mul_f32 v[22:23], v[20:21], v[20:21]
	v_pk_mul_f32 v[58:59], v[18:19], v[18:19]
	s_waitcnt vmcnt(6)
	v_pk_mul_f32 v[60:61], v[28:29], v[28:29]
	v_pk_mul_f32 v[62:63], v[26:27], v[26:27]
	s_waitcnt vmcnt(4)
	v_mul_f32_e32 v64, v35, v35
	v_mul_f32_e32 v66, v37, v37
	v_pk_mov_b32 v[68:69], v[58:59], v[22:23] op_sel:[1,0]
	v_mov_b32_e32 v59, v23
	s_waitcnt vmcnt(3)
	v_pk_mul_f32 v[22:23], v[40:41], v[40:41]
	v_pk_mul_f32 v[70:71], v[38:39], v[38:39]
	v_pk_mov_b32 v[72:73], v[62:63], v[60:61] op_sel:[1,0]
	v_mov_b32_e32 v63, v61
	s_waitcnt vmcnt(2)
	v_pk_mul_f32 v[60:61], v[44:45], v[44:45]
	v_pk_mul_f32 v[74:75], v[42:43], v[42:43]
	v_mul_f32_e32 v77, v32, v32
	v_mul_f32_e32 v79, v33, v33
	v_pk_fma_f32 v[64:65], v[34:35], v[34:35], v[64:65] op_sel_hi:[1,1,0]
	v_pk_fma_f32 v[66:67], v[36:37], v[36:37], v[66:67] op_sel_hi:[1,1,0]
	v_pk_add_f32 v[58:59], v[68:69], v[58:59]
	v_pk_mov_b32 v[68:69], v[70:71], v[22:23] op_sel:[1,0]
	v_mov_b32_e32 v71, v23
	v_pk_add_f32 v[22:23], v[72:73], v[62:63]
	v_pk_mov_b32 v[62:63], v[74:75], v[60:61] op_sel:[1,0]
	v_mov_b32_e32 v75, v61
	s_waitcnt vmcnt(0)
	v_mul_f32_e32 v76, v51, v51
	v_mul_f32_e32 v78, v53, v53
	v_mov_b32_e32 v65, v77
	v_mov_b32_e32 v67, v79
	v_pk_add_f32 v[68:69], v[68:69], v[70:71]
	v_pk_add_f32 v[62:63], v[62:63], v[74:75]
	v_mul_f32_e32 v13, v30, v30
	v_mul_f32_e32 v25, v31, v31
	v_mul_f32_e32 v80, v46, v46
	v_mul_f32_e32 v81, v47, v47
	v_mul_f32_e32 v82, v48, v48
	v_mul_f32_e32 v83, v49, v49
	v_pk_fma_f32 v[60:61], v[50:51], v[50:51], v[76:77] op_sel_hi:[1,1,0]
	v_pk_fma_f32 v[72:73], v[52:53], v[52:53], v[78:79] op_sel_hi:[1,1,0]
	v_pk_add_f32 v[58:59], v[58:59], v[58:59] op_sel:[0,1] op_sel_hi:[1,0]
	v_pk_add_f32 v[22:23], v[22:23], v[22:23] op_sel:[0,1] op_sel_hi:[1,0]
	v_pk_add_f32 v[64:65], v[64:65], v[66:67]
	v_pk_add_f32 v[66:67], v[68:69], v[68:69] op_sel:[0,1] op_sel_hi:[1,0]
	v_pk_add_f32 v[62:63], v[62:63], v[62:63] op_sel:[0,1] op_sel_hi:[1,0]
	v_mov_b32_e32 v61, v82
	v_mov_b32_e32 v73, v83
	v_mov_b32_e32 v59, v13
	v_mov_b32_e32 v23, v25
	v_mov_b32_e32 v67, v80
	v_mov_b32_e32 v63, v81
	v_pk_add_f32 v[60:61], v[60:61], v[72:73]
	v_pk_add_f32 v[22:23], v[58:59], v[22:23]
	v_pk_add_f32 v[58:59], v[66:67], v[62:63]
	v_pk_add_f32 v[22:23], v[22:23], v[64:65]
	v_pk_add_f32 v[58:59], v[58:59], v[60:61]
	v_mov_b32_e32 v61, v22
	v_mov_b32_e32 v60, v58
	v_mov_b32_e32 v22, v59
	v_pk_add_f32 v[22:23], v[60:61], v[22:23]
	ds_bpermute_b32 v59, v7, v23
	ds_bpermute_b32 v58, v7, v22
	s_waitcnt lgkmcnt(0)
	v_pk_add_f32 v[22:23], v[22:23], v[58:59]
	ds_bpermute_b32 v59, v8, v23
	ds_bpermute_b32 v58, v8, v22
	s_waitcnt lgkmcnt(0)
	v_pk_add_f32 v[22:23], v[22:23], v[58:59]
	ds_bpermute_b32 v59, v9, v23
	ds_bpermute_b32 v58, v9, v22
	s_waitcnt lgkmcnt(0)
; __device__ __forceinline__ unsigned pk_bf16(float lo, float hi) { typedef __bf16 b2 __attribute__((ext_vector_type(2))); f32x2 v = {lo, hi}; b2 b = __builtin_convertvector(v, b2); return __builtin_bit_cast(unsigned, b); }
; __device__ __forceinline__ void p0_prologue(const Ptrs& P, LAS unsigned char* lds, int vcu, int G) {
;     ...
;         const float rstd = rsqrtf(wave_sum(s) * (1.0f / DM) + NORM_EPS), rstd2 = rsqrtf(wave_sum(s2) * (1.0f / DM) + NORM_EPS);
;         u32x2* o8 = (u32x2*)(H + (size_t)m * DM) + lane; u32x2* o82 = (u32x2*)(H + (size_t)m2 * DM) + lane;
; #pragma unroll
;         for (int j = 0; j < 4; ++j) { const f32x4 w4 = ((const f32x4*)P.norm_w)[lane + 64 * j];
;             o8[64 * j] = (u32x2){pk_bf16(v[j].x * rstd * w4.x, v[j].y * rstd * w4.y), pk_bf16(v[j].z * rstd * w4.z, v[j].w * rstd * w4.w)};
;             o82[64 * j] = (u32x2){pk_bf16(v2[j].x * rstd2 * w4.x, v2[j].y * rstd2 * w4.y), pk_bf16(v2[j].z * rstd2 * w4.z, v2[j].w * rstd2 * w4.w)}; }
	v_pk_add_f32 v[22:23], v[22:23], v[58:59]
	ds_bpermute_b32 v59, v10, v23
	ds_bpermute_b32 v58, v10, v22
	s_waitcnt lgkmcnt(0)
	v_pk_add_f32 v[22:23], v[22:23], v[58:59]
	ds_bpermute_b32 v59, v11, v23
	ds_bpermute_b32 v58, v11, v22
	s_waitcnt lgkmcnt(0)
	v_pk_add_f32 v[22:23], v[22:23], v[58:59]
	ds_bpermute_b32 v59, v12, v23
	ds_bpermute_b32 v58, v12, v22
	s_waitcnt lgkmcnt(0)
	v_pk_add_f32 v[22:23], v[22:23], v[58:59]
	s_nop 0
	v_pk_fma_f32 v[22:23], v[22:23], s[6:7], v[6:7] op_sel_hi:[1,0,0]
	s_nop 0
	v_mul_f32_e32 v13, 0x4b800000, v23
	v_cmp_gt_f32_e64 s[0:1], s7, v23
	v_mul_f32_e32 v25, 0x4b800000, v22
	v_cmp_gt_f32_e32 vcc, s7, v22
	v_cndmask_b32_e64 v13, v23, v13, s[0:1]
	v_rsq_f32_e32 v13, v13
	v_cndmask_b32_e32 v22, v22, v25, vcc
	v_rsq_f32_e32 v23, v22
	v_mul_f32_e32 v22, 0x45800000, v13
	v_cndmask_b32_e64 v22, v13, v22, s[0:1]
	v_mul_f32_e32 v25, 0x45800000, v23
	v_cndmask_b32_e32 v58, v23, v25, vcc
	v_pk_mul_f32 v[18:19], v[18:19], v[22:23] op_sel_hi:[1,0]
	v_pk_mul_f32 v[20:21], v[20:21], v[22:23] op_sel_hi:[1,0]
	v_pk_mul_f32 v[38:39], v[38:39], v[58:59] op_sel_hi:[1,0]
	v_pk_mul_f32 v[40:41], v[40:41], v[58:59] op_sel_hi:[1,0]
	v_pk_mul_f32 v[18:19], v[100:101], v[18:19]
	v_pk_mul_f32 v[20:21], v[102:103], v[20:21]
	v_pk_mul_f32 v[14:15], v[100:101], v[38:39]
	v_pk_mul_f32 v[16:17], v[102:103], v[40:41]
	v_cvt_pk_bf16_f32 v18, v18, v19
	v_cvt_pk_bf16_f32 v19, v20, v21
	v_cvt_pk_bf16_f32 v14, v14, v15
	v_cvt_pk_bf16_f32 v15, v16, v17
	global_store_dwordx2 v[54:55], v[18:19], off sc1
	global_store_dwordx2 v[56:57], v[14:15], off sc1
	v_pk_mul_f32 v[18:19], v[26:27], v[22:23] op_sel_hi:[1,0]
	v_pk_mul_f32 v[20:21], v[28:29], v[22:23] op_sel_hi:[1,0]
	v_pk_mul_f32 v[26:27], v[42:43], v[58:59] op_sel_hi:[1,0]
	v_pk_mul_f32 v[28:29], v[44:45], v[58:59] op_sel_hi:[1,0]
	s_add_i32 s0, s8, s17
	s_cmpk_gt_i32 s0, 0x3fff
	v_pk_mul_f32 v[18:19], v[104:105], v[18:19]
	v_pk_mul_f32 v[20:21], v[106:107], v[20:21]
	v_pk_mul_f32 v[14:15], v[104:105], v[26:27]
	v_pk_mul_f32 v[16:17], v[106:107], v[28:29]
	v_cvt_pk_bf16_f32 v18, v18, v19
	v_cvt_pk_bf16_f32 v19, v20, v21
	v_cvt_pk_bf16_f32 v14, v14, v15
	v_cvt_pk_bf16_f32 v15, v16, v17
	global_store_dwordx2 v[54:55], v[18:19], off offset:512 sc1
	global_store_dwordx2 v[56:57], v[14:15], off offset:512 sc1
	v_pk_mul_f32 v[18:19], v[34:35], v[22:23] op_sel_hi:[1,0]
	v_pk_mul_f32 v[20:21], v[36:37], v[22:23] op_sel_hi:[1,0]
	v_pk_mul_f32 v[26:27], v[50:51], v[58:59] op_sel_hi:[1,0]
	v_pk_mul_f32 v[28:29], v[52:53], v[58:59] op_sel_hi:[1,0]
	v_pk_mul_f32 v[18:19], v[18:19], v[108:109]
	v_pk_mul_f32 v[20:21], v[20:21], v[110:111]
	v_pk_mul_f32 v[14:15], v[108:109], v[26:27]
	v_pk_mul_f32 v[16:17], v[110:111], v[28:29]
	v_cvt_pk_bf16_f32 v18, v18, v19
	v_cvt_pk_bf16_f32 v19, v20, v21
	v_cvt_pk_bf16_f32 v14, v14, v15
	v_cvt_pk_bf16_f32 v15, v16, v17
	global_store_dwordx2 v[54:55], v[18:19], off offset:1024 sc1
	global_store_dwordx2 v[56:57], v[14:15], off offset:1024 sc1
	v_pk_mul_f32 v[18:19], v[30:31], v[22:23] op_sel_hi:[1,0]
	v_pk_mul_f32 v[20:21], v[32:33], v[22:23] op_sel_hi:[1,0]
	v_pk_mul_f32 v[22:23], v[46:47], v[58:59] op_sel_hi:[1,0]
	v_pk_mul_f32 v[26:27], v[48:49], v[58:59] op_sel_hi:[1,0]
	v_pk_mul_f32 v[18:19], v[18:19], v[112:113]
	v_pk_mul_f32 v[20:21], v[20:21], v[114:115]
	v_pk_mul_f32 v[14:15], v[22:23], v[112:113]
	v_pk_mul_f32 v[16:17], v[26:27], v[114:115]
	v_cvt_pk_bf16_f32 v18, v18, v19
	v_cvt_pk_bf16_f32 v19, v20, v21
	v_cvt_pk_bf16_f32 v14, v14, v15
	v_cvt_pk_bf16_f32 v15, v16, v17
	global_store_dwordx2 v[54:55], v[18:19], off offset:1536 sc1
	global_store_dwordx2 v[56:57], v[14:15], off offset:1536 sc1
	s_cbranch_scc0 .LBB0_57
